# LN epilogues: H (bf16, re-read by the next GEMM on the same XCD) stored plain again; X stays write-through
# speedup vs baseline: 1.0001x; 1.0001x over previous
.Lln1_pok1:
	v_add_f32_e32 v250, v250, v226
	v_add_f32_e32 v252, v252, v228
	v_add_f32_e32 v250, v250, v230
	v_add_f32_e32 v252, v252, v232
	v_add_f32_e32 v250, v250, v234
	v_add_f32_e32 v252, v252, v236
	v_add_f32_e32 v250, v250, v238
	v_add_f32_e32 v252, v252, v240
	v_add_f32_e32 v250, v250, v206
	v_add_f32_e32 v252, v252, v208
	v_add_f32_e32 v250, v250, v210
	v_add_f32_e32 v252, v252, v212
	v_add_f32_e32 v250, v250, v214
	v_add_f32_e32 v252, v252, v216
	v_add_f32_e32 v250, v250, v218
	v_add_f32_e32 v252, v252, v220
	global_load_dwordx4 v[226:229], v246, s[22:23]
	global_load_dwordx4 v[230:233], v246, s[22:23] offset:64
	global_load_dwordx4 v[234:237], v246, s[22:23] offset:128
	global_load_dwordx4 v[238:241], v246, s[22:23] offset:192
	v_mov_b32_e32 v206, v250
	v_mov_b32_e32 v207, v252
	v_mul_f32_e32 v208, 0x3a800000, v206
	v_mul_f32_e32 v209, v208, v208
	v_mov_b32_e32 v216, 0x3a800000
	v_fma_f32 v209, v207, v216, -v209
	v_max_f32_e32 v209, 0, v209
	v_add_f32_e32 v209, 0x3727c5ac, v209
	v_rsq_f32_e32 v209, v209
	v_mov_b32_e32 v210, v208
	v_mov_b32_e32 v211, v208
	v_mov_b32_e32 v214, v209
	v_mov_b32_e32 v215, v209
	s_nop 1
	v_permlane16_swap_b32_e32 v210, v211
	v_permlane16_swap_b32_e32 v214, v215
	v_mov_b32_e32 v212, v210
	v_mov_b32_e32 v213, v211
	v_mov_b32_e32 v216, v214
	v_mov_b32_e32 v217, v215
	s_nop 1
	v_permlane32_swap_b32_e32 v210, v212
	v_permlane32_swap_b32_e32 v211, v213
	v_permlane32_swap_b32_e32 v214, v216
	v_permlane32_swap_b32_e32 v215, v217
	v_readfirstlane_b32 s64, v137
	s_lshr_b32 s64, s64, 6
	s_lshl_b32 s64, s64, 14
	v_and_b32_e32 v222, 63, v137
	v_and_b32_e32 v246, 15, v222
	v_lshrrev_b32_e32 v247, 4, v222
	v_and_b32_e32 v248, 3, v246
	v_xor_b32_e32 v248, v248, v247
	v_lshlrev_b32_e32 v248, 4, v248
	v_lshl_add_u32 v248, v246, 8, v248
	v_add_u32_e32 v248, s64, v248
	v_lshl_add_u32 v249, v222, 4, s64
	v_add_u32_e32 v250, s36, v247
	v_lshlrev_b32_e32 v250, 12, v250
	v_xor_b32_e32 v251, v246, v247
	v_lshl_add_u32 v250, v251, 4, v250
	s_lshl_b32 s65, s37, 2
	v_add_u32_e32 v250, s65, v250
	v_sub_f32_e32 v62, v62, v210
	v_sub_f32_e32 v63, v63, v210
	v_sub_f32_e32 v64, v64, v210
	v_sub_f32_e32 v65, v65, v210
	v_mul_f32_e32 v62, v214, v62
	v_mul_f32_e32 v63, v214, v63
	v_mul_f32_e32 v64, v214, v64
	v_mul_f32_e32 v65, v214, v65
	v_fma_f32 v62, v66, v62, v90
	v_fma_f32 v63, v67, v63, v91
	v_fma_f32 v64, v68, v64, v92
	v_fma_f32 v65, v69, v65, v93
	ds_write_b128 v248, v[62:65] offset:0
	v_sub_f32_e32 v86, v86, v210
	v_sub_f32_e32 v87, v87, v210
	v_sub_f32_e32 v88, v88, v210
	v_sub_f32_e32 v89, v89, v210
	v_mul_f32_e32 v86, v214, v86
	v_mul_f32_e32 v87, v214, v87
	v_mul_f32_e32 v88, v214, v88
	v_mul_f32_e32 v89, v214, v89
	v_fma_f32 v86, v74, v86, v94
	v_fma_f32 v87, v75, v87, v95
	v_fma_f32 v88, v76, v88, v96
	v_fma_f32 v89, v77, v89, v97
	ds_write_b128 v248, v[86:89] offset:64
	v_sub_f32_e32 v70, v70, v210
	v_sub_f32_e32 v71, v71, v210
	v_sub_f32_e32 v72, v72, v210
	v_sub_f32_e32 v73, v73, v210
	v_mul_f32_e32 v70, v214, v70
	v_mul_f32_e32 v71, v214, v71
	v_mul_f32_e32 v72, v214, v72
	v_mul_f32_e32 v73, v214, v73
	v_fma_f32 v70, v78, v70, v108
	v_fma_f32 v71, v79, v71, v109
	v_fma_f32 v72, v80, v72, v110
	v_fma_f32 v73, v81, v73, v111
	ds_write_b128 v248, v[70:73] offset:128
	v_sub_f32_e32 v176, v176, v210
	v_sub_f32_e32 v177, v177, v210
	v_sub_f32_e32 v178, v178, v210
	v_sub_f32_e32 v179, v179, v210
	v_mul_f32_e32 v176, v214, v176
	v_mul_f32_e32 v177, v214, v177
	v_mul_f32_e32 v178, v214, v178
	v_mul_f32_e32 v179, v214, v179
	v_fma_f32 v176, v82, v176, v172
	v_fma_f32 v177, v83, v177, v173
	v_fma_f32 v178, v84, v178, v174
	v_fma_f32 v179, v85, v179, v175
	ds_write_b128 v248, v[176:179] offset:192
	v_sub_f32_e32 v202, v202, v211
	v_sub_f32_e32 v203, v203, v211
	v_sub_f32_e32 v204, v204, v211
	v_sub_f32_e32 v205, v205, v211
	v_mul_f32_e32 v202, v215, v202
	v_mul_f32_e32 v203, v215, v203
	v_mul_f32_e32 v204, v215, v204
	v_mul_f32_e32 v205, v215, v205
	v_fma_f32 v202, v66, v202, v90
	v_fma_f32 v203, v67, v203, v91
	v_fma_f32 v204, v68, v204, v92
	v_fma_f32 v205, v69, v205, v93
	ds_write_b128 v248, v[202:205] offset:4096
	v_sub_f32_e32 v54, v54, v211
	v_sub_f32_e32 v55, v55, v211
	v_sub_f32_e32 v56, v56, v211
	v_sub_f32_e32 v57, v57, v211
	v_mul_f32_e32 v54, v215, v54
	v_mul_f32_e32 v55, v215, v55
	v_mul_f32_e32 v56, v215, v56
	v_mul_f32_e32 v57, v215, v57
	v_fma_f32 v54, v74, v54, v94
	v_fma_f32 v55, v75, v55, v95
	v_fma_f32 v56, v76, v56, v96
	v_fma_f32 v57, v77, v57, v97
	ds_write_b128 v248, v[54:57] offset:4160
	v_sub_f32_e32 v58, v58, v211
	v_sub_f32_e32 v59, v59, v211
	v_sub_f32_e32 v60, v60, v211
	v_sub_f32_e32 v61, v61, v211
	v_mul_f32_e32 v58, v215, v58
	v_mul_f32_e32 v59, v215, v59
	v_mul_f32_e32 v60, v215, v60
	v_mul_f32_e32 v61, v215, v61
	v_fma_f32 v58, v78, v58, v108
	v_fma_f32 v59, v79, v59, v109
	v_fma_f32 v60, v80, v60, v110
	v_fma_f32 v61, v81, v61, v111
	ds_write_b128 v248, v[58:61] offset:4224
	v_sub_f32_e32 v34, v34, v211
	v_sub_f32_e32 v35, v35, v211
	v_sub_f32_e32 v36, v36, v211
	v_sub_f32_e32 v37, v37, v211
	v_mul_f32_e32 v34, v215, v34
	v_mul_f32_e32 v35, v215, v35
	v_mul_f32_e32 v36, v215, v36
	v_mul_f32_e32 v37, v215, v37
	v_fma_f32 v34, v82, v34, v172
	v_fma_f32 v35, v83, v35, v173
	v_fma_f32 v36, v84, v36, v174
	v_fma_f32 v37, v85, v37, v175
	ds_write_b128 v248, v[34:37] offset:4288
	v_sub_f32_e32 v30, v30, v212
	v_sub_f32_e32 v31, v31, v212
	v_sub_f32_e32 v32, v32, v212
	v_sub_f32_e32 v33, v33, v212
	v_mul_f32_e32 v30, v216, v30
	v_mul_f32_e32 v31, v216, v31
	v_mul_f32_e32 v32, v216, v32
	v_mul_f32_e32 v33, v216, v33
	v_fma_f32 v30, v66, v30, v90
	v_fma_f32 v31, v67, v31, v91
	v_fma_f32 v32, v68, v32, v92
	v_fma_f32 v33, v69, v33, v93
	ds_write_b128 v248, v[30:33] offset:8192
	v_sub_f32_e32 v26, v26, v212
	v_sub_f32_e32 v27, v27, v212
	v_sub_f32_e32 v28, v28, v212
	v_sub_f32_e32 v29, v29, v212
	v_mul_f32_e32 v26, v216, v26
	v_mul_f32_e32 v27, v216, v27
	v_mul_f32_e32 v28, v216, v28
	v_mul_f32_e32 v29, v216, v29
	v_fma_f32 v26, v74, v26, v94
	v_fma_f32 v27, v75, v27, v95
	v_fma_f32 v28, v76, v28, v96
	v_fma_f32 v29, v77, v29, v97
	ds_write_b128 v248, v[26:29] offset:8256
	v_sub_f32_e32 v22, v22, v212
	v_sub_f32_e32 v23, v23, v212
	v_sub_f32_e32 v24, v24, v212
	v_sub_f32_e32 v25, v25, v212
	v_mul_f32_e32 v22, v216, v22
	v_mul_f32_e32 v23, v216, v23
	v_mul_f32_e32 v24, v216, v24
	v_mul_f32_e32 v25, v216, v25
	v_fma_f32 v22, v78, v22, v108
	v_fma_f32 v23, v79, v23, v109
	v_fma_f32 v24, v80, v24, v110
	v_fma_f32 v25, v81, v25, v111
	ds_write_b128 v248, v[22:25] offset:8320
	v_sub_f32_e32 v18, v18, v212
	v_sub_f32_e32 v19, v19, v212
	v_sub_f32_e32 v20, v20, v212
	v_sub_f32_e32 v21, v21, v212
	v_mul_f32_e32 v18, v216, v18
	v_mul_f32_e32 v19, v216, v19
	v_mul_f32_e32 v20, v216, v20
	v_mul_f32_e32 v21, v216, v21
	v_fma_f32 v18, v82, v18, v172
	v_fma_f32 v19, v83, v19, v173
	v_fma_f32 v20, v84, v20, v174
	v_fma_f32 v21, v85, v21, v175
	ds_write_b128 v248, v[18:21] offset:8384
	v_sub_f32_e32 v14, v14, v213
	v_sub_f32_e32 v15, v15, v213
	v_sub_f32_e32 v16, v16, v213
	v_sub_f32_e32 v17, v17, v213
	v_mul_f32_e32 v14, v217, v14
	v_mul_f32_e32 v15, v217, v15
	v_mul_f32_e32 v16, v217, v16
	v_mul_f32_e32 v17, v217, v17
	v_fma_f32 v14, v66, v14, v90
	v_fma_f32 v15, v67, v15, v91
	v_fma_f32 v16, v68, v16, v92
	v_fma_f32 v17, v69, v17, v93
	ds_write_b128 v248, v[14:17] offset:12288
	v_sub_f32_e32 v10, v10, v213
	v_sub_f32_e32 v11, v11, v213
	v_sub_f32_e32 v12, v12, v213
	v_sub_f32_e32 v13, v13, v213
	v_mul_f32_e32 v10, v217, v10
	v_mul_f32_e32 v11, v217, v11
	v_mul_f32_e32 v12, v217, v12
	v_mul_f32_e32 v13, v217, v13
	v_fma_f32 v10, v74, v10, v94
	v_fma_f32 v11, v75, v11, v95
	v_fma_f32 v12, v76, v12, v96
	v_fma_f32 v13, v77, v13, v97
	ds_write_b128 v248, v[10:13] offset:12352
	v_sub_f32_e32 v6, v6, v213
	v_sub_f32_e32 v7, v7, v213
	v_sub_f32_e32 v8, v8, v213
	v_sub_f32_e32 v9, v9, v213
	v_mul_f32_e32 v6, v217, v6
	v_mul_f32_e32 v7, v217, v7
	v_mul_f32_e32 v8, v217, v8
	v_mul_f32_e32 v9, v217, v9
	v_fma_f32 v6, v78, v6, v108
	v_fma_f32 v7, v79, v7, v109
	v_fma_f32 v8, v80, v8, v110
	v_fma_f32 v9, v81, v9, v111
	ds_write_b128 v248, v[6:9] offset:12416
	v_sub_f32_e32 v2, v2, v213
	v_sub_f32_e32 v3, v3, v213
	v_sub_f32_e32 v4, v4, v213
	v_sub_f32_e32 v5, v5, v213
	v_mul_f32_e32 v2, v217, v2
	v_mul_f32_e32 v3, v217, v3
	v_mul_f32_e32 v4, v217, v4
	v_mul_f32_e32 v5, v217, v5
	v_fma_f32 v2, v82, v2, v172
	v_fma_f32 v3, v83, v3, v173
	v_fma_f32 v4, v84, v4, v174
	v_fma_f32 v5, v85, v5, v175
	ds_write_b128 v248, v[2:5] offset:12480
	s_waitcnt lgkmcnt(0)
	ds_read_b128 v[66:69], v249 offset:0
	ds_read_b128 v[74:77], v249 offset:1024
	ds_read_b128 v[78:81], v249 offset:2048
	ds_read_b128 v[82:85], v249 offset:3072
	ds_read_b128 v[90:93], v249 offset:4096
	ds_read_b128 v[94:97], v249 offset:5120
	ds_read_b128 v[108:111], v249 offset:6144
	ds_read_b128 v[172:175], v249 offset:7168
	s_waitcnt lgkmcnt(7)
	global_store_dwordx4 v250, v[66:69], s[26:27] sc1
	s_waitcnt lgkmcnt(6)
	v_add_u32_e32 v251, 0x4000, v250
	global_store_dwordx4 v251, v[74:77], s[26:27] sc1
	s_waitcnt lgkmcnt(5)
	v_add_u32_e32 v251, 0x8000, v250
	global_store_dwordx4 v251, v[78:81], s[26:27] sc1
	s_waitcnt lgkmcnt(4)
	v_add_u32_e32 v251, 0xc000, v250
	global_store_dwordx4 v251, v[82:85], s[26:27] sc1
	s_waitcnt lgkmcnt(3)
	v_add_u32_e32 v251, 0x10000, v250
	global_store_dwordx4 v251, v[90:93], s[26:27] sc1
	s_waitcnt lgkmcnt(2)
	v_add_u32_e32 v251, 0x14000, v250
	global_store_dwordx4 v251, v[94:97], s[26:27] sc1
	s_waitcnt lgkmcnt(1)
	v_add_u32_e32 v251, 0x18000, v250
	global_store_dwordx4 v251, v[108:111], s[26:27] sc1
	s_waitcnt lgkmcnt(0)
	v_add_u32_e32 v251, 0x1c000, v250
	global_store_dwordx4 v251, v[172:175], s[26:27] sc1
	s_nop 1
	ds_read_b128 v[66:69], v249 offset:8192
	ds_read_b128 v[74:77], v249 offset:9216
	ds_read_b128 v[78:81], v249 offset:10240
	ds_read_b128 v[82:85], v249 offset:11264
	ds_read_b128 v[90:93], v249 offset:12288
	ds_read_b128 v[94:97], v249 offset:13312
	ds_read_b128 v[108:111], v249 offset:14336
	ds_read_b128 v[172:175], v249 offset:15360
	s_waitcnt lgkmcnt(7)
	v_add_u32_e32 v251, 0x20000, v250
	global_store_dwordx4 v251, v[66:69], s[26:27] sc1
	s_waitcnt lgkmcnt(6)
	v_add_u32_e32 v251, 0x24000, v250
	global_store_dwordx4 v251, v[74:77], s[26:27] sc1
	s_waitcnt lgkmcnt(5)
	v_add_u32_e32 v251, 0x28000, v250
	global_store_dwordx4 v251, v[78:81], s[26:27] sc1
	s_waitcnt lgkmcnt(4)
	v_add_u32_e32 v251, 0x2c000, v250
	global_store_dwordx4 v251, v[82:85], s[26:27] sc1
	s_waitcnt lgkmcnt(3)
	v_add_u32_e32 v251, 0x30000, v250
	global_store_dwordx4 v251, v[90:93], s[26:27] sc1
	s_waitcnt lgkmcnt(2)
	v_add_u32_e32 v251, 0x34000, v250
	global_store_dwordx4 v251, v[94:97], s[26:27] sc1
	s_waitcnt lgkmcnt(1)
	v_add_u32_e32 v251, 0x38000, v250
	global_store_dwordx4 v251, v[108:111], s[26:27] sc1
	s_waitcnt lgkmcnt(0)
	v_add_u32_e32 v251, 0x3c000, v250
	global_store_dwordx4 v251, v[172:175], s[26:27] sc1
	s_nop 1
	s_add_u32 s44, s94, 0x7b48000
	s_addc_u32 s45, s95, 0
	s_waitcnt vmcnt(16)
	v_add_f32_e32 v226, 1.0, v226
	v_add_f32_e32 v227, 1.0, v227
	v_add_f32_e32 v228, 1.0, v228
	v_add_f32_e32 v229, 1.0, v229
	v_add_f32_e32 v230, 1.0, v230
	v_add_f32_e32 v231, 1.0, v231
	v_add_f32_e32 v232, 1.0, v232
	v_add_f32_e32 v233, 1.0, v233
	v_add_f32_e32 v234, 1.0, v234
	v_add_f32_e32 v235, 1.0, v235
	v_add_f32_e32 v236, 1.0, v236
	v_add_f32_e32 v237, 1.0, v237
	v_add_f32_e32 v238, 1.0, v238
	v_add_f32_e32 v239, 1.0, v239
	v_add_f32_e32 v240, 1.0, v240
	v_add_f32_e32 v241, 1.0, v241
	v_and_b32_e32 v251, 7, v246
	v_lshlrev_b32_e32 v251, 1, v251
	v_or_b32_e32 v218, 0, v247
	v_xor_b32_e32 v218, v218, v251
	v_lshlrev_b32_e32 v218, 3, v218
	v_lshl_add_u32 v218, v246, 7, v218
	v_add_u32_e32 v218, s64, v218
	v_or_b32_e32 v219, 4, v247
	v_xor_b32_e32 v219, v219, v251
	v_lshlrev_b32_e32 v219, 3, v219
	v_lshl_add_u32 v219, v246, 7, v219
	v_add_u32_e32 v219, s64, v219
	v_or_b32_e32 v220, 8, v247
	v_xor_b32_e32 v220, v220, v251
	v_lshlrev_b32_e32 v220, 3, v220
	v_lshl_add_u32 v220, v246, 7, v220
	v_add_u32_e32 v220, s64, v220
	v_or_b32_e32 v221, 12, v247
	v_xor_b32_e32 v221, v221, v251
	v_lshlrev_b32_e32 v221, 3, v221
	v_lshl_add_u32 v221, v246, 7, v221
	v_add_u32_e32 v221, s64, v221
	v_lshrrev_b32_e32 v248, 3, v222
	v_and_b32_e32 v251, 7, v222
	v_xor_b32_e32 v251, v251, v248
	v_add_u32_e32 v248, s36, v248
	v_lshlrev_b32_e32 v248, 11, v248
	v_lshl_add_u32 v248, v251, 4, v248
	s_lshl_b32 s65, s37, 1
	v_add_u32_e32 v248, s65, v248
	v_fma_f32 v62, v226, v62, v38
	v_fma_f32 v63, v227, v63, v39
	v_fma_f32 v64, v228, v64, v40
	v_fma_f32 v65, v229, v65, v41
	v_cvt_pk_bf16_f32 v62, v62, v63
	v_cvt_pk_bf16_f32 v63, v64, v65
	ds_write_b64 v218, v[62:63] offset:0
	v_fma_f32 v86, v230, v86, v42
	v_fma_f32 v87, v231, v87, v43
	v_fma_f32 v88, v232, v88, v44
	v_fma_f32 v89, v233, v89, v45
	v_cvt_pk_bf16_f32 v86, v86, v87
	v_cvt_pk_bf16_f32 v87, v88, v89
	ds_write_b64 v219, v[86:87] offset:0
	v_fma_f32 v70, v234, v70, v46
	v_fma_f32 v71, v235, v71, v47
	v_fma_f32 v72, v236, v72, v48
	v_fma_f32 v73, v237, v73, v49
	v_cvt_pk_bf16_f32 v70, v70, v71
	v_cvt_pk_bf16_f32 v71, v72, v73
	ds_write_b64 v220, v[70:71] offset:0
	v_fma_f32 v176, v238, v176, v50
	v_fma_f32 v177, v239, v177, v51
	v_fma_f32 v178, v240, v178, v52
	v_fma_f32 v179, v241, v179, v53
	v_cvt_pk_bf16_f32 v176, v176, v177
	v_cvt_pk_bf16_f32 v177, v178, v179
	ds_write_b64 v221, v[176:177] offset:0
	v_fma_f32 v202, v226, v202, v38
	v_fma_f32 v203, v227, v203, v39
	v_fma_f32 v204, v228, v204, v40
	v_fma_f32 v205, v229, v205, v41
	v_cvt_pk_bf16_f32 v202, v202, v203
	v_cvt_pk_bf16_f32 v203, v204, v205
	ds_write_b64 v218, v[202:203] offset:2048
	v_fma_f32 v54, v230, v54, v42
	v_fma_f32 v55, v231, v55, v43
	v_fma_f32 v56, v232, v56, v44
	v_fma_f32 v57, v233, v57, v45
	v_cvt_pk_bf16_f32 v54, v54, v55
	v_cvt_pk_bf16_f32 v55, v56, v57
	ds_write_b64 v219, v[54:55] offset:2048
	v_fma_f32 v58, v234, v58, v46
	v_fma_f32 v59, v235, v59, v47
	v_fma_f32 v60, v236, v60, v48
	v_fma_f32 v61, v237, v61, v49
	v_cvt_pk_bf16_f32 v58, v58, v59
	v_cvt_pk_bf16_f32 v59, v60, v61
	ds_write_b64 v220, v[58:59] offset:2048
	v_fma_f32 v34, v238, v34, v50
	v_fma_f32 v35, v239, v35, v51
	v_fma_f32 v36, v240, v36, v52
	v_fma_f32 v37, v241, v37, v53
	v_cvt_pk_bf16_f32 v34, v34, v35
	v_cvt_pk_bf16_f32 v35, v36, v37
	ds_write_b64 v221, v[34:35] offset:2048
	v_fma_f32 v30, v226, v30, v38
	v_fma_f32 v31, v227, v31, v39
	v_fma_f32 v32, v228, v32, v40
	v_fma_f32 v33, v229, v33, v41
	v_cvt_pk_bf16_f32 v30, v30, v31
	v_cvt_pk_bf16_f32 v31, v32, v33
	ds_write_b64 v218, v[30:31] offset:4096
	v_fma_f32 v26, v230, v26, v42
	v_fma_f32 v27, v231, v27, v43
	v_fma_f32 v28, v232, v28, v44
	v_fma_f32 v29, v233, v29, v45
	v_cvt_pk_bf16_f32 v26, v26, v27
	v_cvt_pk_bf16_f32 v27, v28, v29
	ds_write_b64 v219, v[26:27] offset:4096
	v_fma_f32 v22, v234, v22, v46
	v_fma_f32 v23, v235, v23, v47
	v_fma_f32 v24, v236, v24, v48
	v_fma_f32 v25, v237, v25, v49
	v_cvt_pk_bf16_f32 v22, v22, v23
	v_cvt_pk_bf16_f32 v23, v24, v25
	ds_write_b64 v220, v[22:23] offset:4096
	v_fma_f32 v18, v238, v18, v50
	v_fma_f32 v19, v239, v19, v51
	v_fma_f32 v20, v240, v20, v52
	v_fma_f32 v21, v241, v21, v53
	v_cvt_pk_bf16_f32 v18, v18, v19
	v_cvt_pk_bf16_f32 v19, v20, v21
	ds_write_b64 v221, v[18:19] offset:4096
	v_fma_f32 v14, v226, v14, v38
	v_fma_f32 v15, v227, v15, v39
	v_fma_f32 v16, v228, v16, v40
	v_fma_f32 v17, v229, v17, v41
	v_cvt_pk_bf16_f32 v14, v14, v15
	v_cvt_pk_bf16_f32 v15, v16, v17
	ds_write_b64 v218, v[14:15] offset:6144
	v_fma_f32 v10, v230, v10, v42
	v_fma_f32 v11, v231, v11, v43
	v_fma_f32 v12, v232, v12, v44
	v_fma_f32 v13, v233, v13, v45
	v_cvt_pk_bf16_f32 v10, v10, v11
	v_cvt_pk_bf16_f32 v11, v12, v13
	ds_write_b64 v219, v[10:11] offset:6144
	v_fma_f32 v6, v234, v6, v46
	v_fma_f32 v7, v235, v7, v47
	v_fma_f32 v8, v236, v8, v48
	v_fma_f32 v9, v237, v9, v49
	v_cvt_pk_bf16_f32 v6, v6, v7
	v_cvt_pk_bf16_f32 v7, v8, v9
	ds_write_b64 v220, v[6:7] offset:6144
	v_fma_f32 v2, v238, v2, v50
	v_fma_f32 v3, v239, v3, v51
	v_fma_f32 v4, v240, v4, v52
	v_fma_f32 v5, v241, v5, v53
	v_cvt_pk_bf16_f32 v2, v2, v3
	v_cvt_pk_bf16_f32 v3, v4, v5
	ds_write_b64 v221, v[2:3] offset:6144
	s_waitcnt lgkmcnt(0)
	ds_read_b128 v[66:69], v249 offset:0
	ds_read_b128 v[74:77], v249 offset:1024
	ds_read_b128 v[78:81], v249 offset:2048
	ds_read_b128 v[82:85], v249 offset:3072
	ds_read_b128 v[90:93], v249 offset:4096
	ds_read_b128 v[94:97], v249 offset:5120
	ds_read_b128 v[108:111], v249 offset:6144
	ds_read_b128 v[172:175], v249 offset:7168
	s_waitcnt lgkmcnt(7)
	global_store_dwordx4 v248, v[66:69], s[44:45]
	s_waitcnt lgkmcnt(6)
	v_add_u32_e32 v251, 0x4000, v248
	global_store_dwordx4 v251, v[74:77], s[44:45]
	s_waitcnt lgkmcnt(5)
	v_add_u32_e32 v251, 0x8000, v248
	global_store_dwordx4 v251, v[78:81], s[44:45]
	s_waitcnt lgkmcnt(4)
	v_add_u32_e32 v251, 0xc000, v248
	global_store_dwordx4 v251, v[82:85], s[44:45]
	s_waitcnt lgkmcnt(3)
	v_add_u32_e32 v251, 0x10000, v248
	global_store_dwordx4 v251, v[90:93], s[44:45]
	s_waitcnt lgkmcnt(2)
	v_add_u32_e32 v251, 0x14000, v248
	global_store_dwordx4 v251, v[94:97], s[44:45]
	s_waitcnt lgkmcnt(1)
	v_add_u32_e32 v251, 0x18000, v248
	global_store_dwordx4 v251, v[108:111], s[44:45]
	s_waitcnt lgkmcnt(0)
	v_add_u32_e32 v251, 0x1c000, v248
	global_store_dwordx4 v251, v[172:175], s[44:45]
	v_readlane_b32 s78, v255, 33
	v_readlane_b32 s79, v255, 34
	s_barrier
	s_load_dword s6, s[78:79], 0x0
	s_mov_b64 s[76:77], 0x7b4c180
	s_mov_b64 s[68:69], 0x7b54180
	s_mov_b64 s[74:75], 0x68800
	s_waitcnt lgkmcnt(0)
	s_add_i32 s60, s6, s60
	s_cmpk_gt_i32 s60, 0xbf
	s_cbranch_scc0 .LBB0_93

.Lln2_nomod:
	v_mov_b32_e32 v206, v250
	v_mov_b32_e32 v207, v252
	v_mul_f32_e32 v208, 0x3a800000, v206
	v_mul_f32_e32 v209, v208, v208
	v_mov_b32_e32 v216, 0x3a800000
	v_fma_f32 v209, v207, v216, -v209
	v_max_f32_e32 v209, 0, v209
	v_add_f32_e32 v209, 0x3727c5ac, v209
	v_rsq_f32_e32 v209, v209
	v_mov_b32_e32 v210, v208
	v_mov_b32_e32 v211, v208
	v_mov_b32_e32 v214, v209
	v_mov_b32_e32 v215, v209
	s_nop 1
	v_permlane16_swap_b32_e32 v210, v211
	v_permlane16_swap_b32_e32 v214, v215
	v_mov_b32_e32 v212, v210
	v_mov_b32_e32 v213, v211
	v_mov_b32_e32 v216, v214
	v_mov_b32_e32 v217, v215
	s_nop 1
	v_permlane32_swap_b32_e32 v210, v212
	v_permlane32_swap_b32_e32 v211, v213
	v_permlane32_swap_b32_e32 v214, v216
	v_permlane32_swap_b32_e32 v215, v217
	s_cmp_eq_u32 s53, 3
	s_cselect_b32 s26, s92, s26
	s_cselect_b32 s27, s93, s27
	v_readfirstlane_b32 s54, v137
	s_lshr_b32 s54, s54, 6
	s_lshl_b32 s54, s54, 14
	v_and_b32_e32 v222, 63, v137
	v_and_b32_e32 v246, 15, v222
	v_lshrrev_b32_e32 v247, 4, v222
	v_and_b32_e32 v248, 3, v246
	v_xor_b32_e32 v248, v248, v247
	v_lshlrev_b32_e32 v248, 4, v248
	v_lshl_add_u32 v248, v246, 8, v248
	v_add_u32_e32 v248, s54, v248
	v_lshl_add_u32 v249, v222, 4, s54
	v_add_u32_e32 v250, s50, v247
	v_lshlrev_b32_e32 v250, 12, v250
	v_xor_b32_e32 v251, v246, v247
	v_lshl_add_u32 v250, v251, 4, v250
	s_lshl_b32 s55, s51, 2
	v_add_u32_e32 v250, s55, v250
	v_sub_f32_e32 v62, v62, v210
	v_sub_f32_e32 v63, v63, v210
	v_sub_f32_e32 v64, v64, v210
	v_sub_f32_e32 v65, v65, v210
	v_mul_f32_e32 v62, v214, v62
	v_mul_f32_e32 v63, v214, v63
	v_mul_f32_e32 v64, v214, v64
	v_mul_f32_e32 v65, v214, v65
	v_fma_f32 v62, v66, v62, v90
	v_fma_f32 v63, v67, v63, v91
	v_fma_f32 v64, v68, v64, v92
	v_fma_f32 v65, v69, v65, v93
	ds_write_b128 v248, v[62:65] offset:0
	v_sub_f32_e32 v86, v86, v210
	v_sub_f32_e32 v87, v87, v210
	v_sub_f32_e32 v88, v88, v210
	v_sub_f32_e32 v89, v89, v210
	v_mul_f32_e32 v86, v214, v86
	v_mul_f32_e32 v87, v214, v87
	v_mul_f32_e32 v88, v214, v88
	v_mul_f32_e32 v89, v214, v89
	v_fma_f32 v86, v74, v86, v94
	v_fma_f32 v87, v75, v87, v95
	v_fma_f32 v88, v76, v88, v96
	v_fma_f32 v89, v77, v89, v97
	ds_write_b128 v248, v[86:89] offset:64
	v_sub_f32_e32 v70, v70, v210
	v_sub_f32_e32 v71, v71, v210
	v_sub_f32_e32 v72, v72, v210
	v_sub_f32_e32 v73, v73, v210
	v_mul_f32_e32 v70, v214, v70
	v_mul_f32_e32 v71, v214, v71
	v_mul_f32_e32 v72, v214, v72
	v_mul_f32_e32 v73, v214, v73
	v_fma_f32 v70, v78, v70, v108
	v_fma_f32 v71, v79, v71, v109
	v_fma_f32 v72, v80, v72, v110
	v_fma_f32 v73, v81, v73, v111
	ds_write_b128 v248, v[70:73] offset:128
	v_sub_f32_e32 v176, v176, v210
	v_sub_f32_e32 v177, v177, v210
	v_sub_f32_e32 v178, v178, v210
	v_sub_f32_e32 v179, v179, v210
	v_mul_f32_e32 v176, v214, v176
	v_mul_f32_e32 v177, v214, v177
	v_mul_f32_e32 v178, v214, v178
	v_mul_f32_e32 v179, v214, v179
	v_fma_f32 v176, v82, v176, v172
	v_fma_f32 v177, v83, v177, v173
	v_fma_f32 v178, v84, v178, v174
	v_fma_f32 v179, v85, v179, v175
	ds_write_b128 v248, v[176:179] offset:192
	v_sub_f32_e32 v202, v202, v211
	v_sub_f32_e32 v203, v203, v211
	v_sub_f32_e32 v204, v204, v211
	v_sub_f32_e32 v205, v205, v211
	v_mul_f32_e32 v202, v215, v202
	v_mul_f32_e32 v203, v215, v203
	v_mul_f32_e32 v204, v215, v204
	v_mul_f32_e32 v205, v215, v205
	v_fma_f32 v202, v66, v202, v90
	v_fma_f32 v203, v67, v203, v91
	v_fma_f32 v204, v68, v204, v92
	v_fma_f32 v205, v69, v205, v93
	ds_write_b128 v248, v[202:205] offset:4096
	v_sub_f32_e32 v54, v54, v211
	v_sub_f32_e32 v55, v55, v211
	v_sub_f32_e32 v56, v56, v211
	v_sub_f32_e32 v57, v57, v211
	v_mul_f32_e32 v54, v215, v54
	v_mul_f32_e32 v55, v215, v55
	v_mul_f32_e32 v56, v215, v56
	v_mul_f32_e32 v57, v215, v57
	v_fma_f32 v54, v74, v54, v94
	v_fma_f32 v55, v75, v55, v95
	v_fma_f32 v56, v76, v56, v96
	v_fma_f32 v57, v77, v57, v97
	ds_write_b128 v248, v[54:57] offset:4160
	v_sub_f32_e32 v58, v58, v211
	v_sub_f32_e32 v59, v59, v211
	v_sub_f32_e32 v60, v60, v211
	v_sub_f32_e32 v61, v61, v211
	v_mul_f32_e32 v58, v215, v58
	v_mul_f32_e32 v59, v215, v59
	v_mul_f32_e32 v60, v215, v60
	v_mul_f32_e32 v61, v215, v61
	v_fma_f32 v58, v78, v58, v108
	v_fma_f32 v59, v79, v59, v109
	v_fma_f32 v60, v80, v60, v110
	v_fma_f32 v61, v81, v61, v111
	ds_write_b128 v248, v[58:61] offset:4224
	v_sub_f32_e32 v34, v34, v211
	v_sub_f32_e32 v35, v35, v211
	v_sub_f32_e32 v36, v36, v211
	v_sub_f32_e32 v37, v37, v211
	v_mul_f32_e32 v34, v215, v34
	v_mul_f32_e32 v35, v215, v35
	v_mul_f32_e32 v36, v215, v36
	v_mul_f32_e32 v37, v215, v37
	v_fma_f32 v34, v82, v34, v172
	v_fma_f32 v35, v83, v35, v173
	v_fma_f32 v36, v84, v36, v174
	v_fma_f32 v37, v85, v37, v175
	ds_write_b128 v248, v[34:37] offset:4288
	v_sub_f32_e32 v30, v30, v212
	v_sub_f32_e32 v31, v31, v212
	v_sub_f32_e32 v32, v32, v212
	v_sub_f32_e32 v33, v33, v212
	v_mul_f32_e32 v30, v216, v30
	v_mul_f32_e32 v31, v216, v31
	v_mul_f32_e32 v32, v216, v32
	v_mul_f32_e32 v33, v216, v33
	v_fma_f32 v30, v66, v30, v90
	v_fma_f32 v31, v67, v31, v91
	v_fma_f32 v32, v68, v32, v92
	v_fma_f32 v33, v69, v33, v93
	ds_write_b128 v248, v[30:33] offset:8192
	v_sub_f32_e32 v26, v26, v212
	v_sub_f32_e32 v27, v27, v212
	v_sub_f32_e32 v28, v28, v212
	v_sub_f32_e32 v29, v29, v212
	v_mul_f32_e32 v26, v216, v26
	v_mul_f32_e32 v27, v216, v27
	v_mul_f32_e32 v28, v216, v28
	v_mul_f32_e32 v29, v216, v29
	v_fma_f32 v26, v74, v26, v94
	v_fma_f32 v27, v75, v27, v95
	v_fma_f32 v28, v76, v28, v96
	v_fma_f32 v29, v77, v29, v97
	ds_write_b128 v248, v[26:29] offset:8256
	v_sub_f32_e32 v22, v22, v212
	v_sub_f32_e32 v23, v23, v212
	v_sub_f32_e32 v24, v24, v212
	v_sub_f32_e32 v25, v25, v212
	v_mul_f32_e32 v22, v216, v22
	v_mul_f32_e32 v23, v216, v23
	v_mul_f32_e32 v24, v216, v24
	v_mul_f32_e32 v25, v216, v25
	v_fma_f32 v22, v78, v22, v108
	v_fma_f32 v23, v79, v23, v109
	v_fma_f32 v24, v80, v24, v110
	v_fma_f32 v25, v81, v25, v111
	ds_write_b128 v248, v[22:25] offset:8320
	v_sub_f32_e32 v18, v18, v212
	v_sub_f32_e32 v19, v19, v212
	v_sub_f32_e32 v20, v20, v212
	v_sub_f32_e32 v21, v21, v212
	v_mul_f32_e32 v18, v216, v18
	v_mul_f32_e32 v19, v216, v19
	v_mul_f32_e32 v20, v216, v20
	v_mul_f32_e32 v21, v216, v21
	v_fma_f32 v18, v82, v18, v172
	v_fma_f32 v19, v83, v19, v173
	v_fma_f32 v20, v84, v20, v174
	v_fma_f32 v21, v85, v21, v175
	ds_write_b128 v248, v[18:21] offset:8384
	v_sub_f32_e32 v14, v14, v213
	v_sub_f32_e32 v15, v15, v213
	v_sub_f32_e32 v16, v16, v213
	v_sub_f32_e32 v17, v17, v213
	v_mul_f32_e32 v14, v217, v14
	v_mul_f32_e32 v15, v217, v15
	v_mul_f32_e32 v16, v217, v16
	v_mul_f32_e32 v17, v217, v17
	v_fma_f32 v14, v66, v14, v90
	v_fma_f32 v15, v67, v15, v91
	v_fma_f32 v16, v68, v16, v92
	v_fma_f32 v17, v69, v17, v93
	ds_write_b128 v248, v[14:17] offset:12288
	v_sub_f32_e32 v10, v10, v213
	v_sub_f32_e32 v11, v11, v213
	v_sub_f32_e32 v12, v12, v213
	v_sub_f32_e32 v13, v13, v213
	v_mul_f32_e32 v10, v217, v10
	v_mul_f32_e32 v11, v217, v11
	v_mul_f32_e32 v12, v217, v12
	v_mul_f32_e32 v13, v217, v13
	v_fma_f32 v10, v74, v10, v94
	v_fma_f32 v11, v75, v11, v95
	v_fma_f32 v12, v76, v12, v96
	v_fma_f32 v13, v77, v13, v97
	ds_write_b128 v248, v[10:13] offset:12352
	v_sub_f32_e32 v6, v6, v213
	v_sub_f32_e32 v7, v7, v213
	v_sub_f32_e32 v8, v8, v213
	v_sub_f32_e32 v9, v9, v213
	v_mul_f32_e32 v6, v217, v6
	v_mul_f32_e32 v7, v217, v7
	v_mul_f32_e32 v8, v217, v8
	v_mul_f32_e32 v9, v217, v9
	v_fma_f32 v6, v78, v6, v108
	v_fma_f32 v7, v79, v7, v109
	v_fma_f32 v8, v80, v8, v110
	v_fma_f32 v9, v81, v9, v111
	ds_write_b128 v248, v[6:9] offset:12416
	v_sub_f32_e32 v2, v2, v213
	v_sub_f32_e32 v3, v3, v213
	v_sub_f32_e32 v4, v4, v213
	v_sub_f32_e32 v5, v5, v213
	v_mul_f32_e32 v2, v217, v2
	v_mul_f32_e32 v3, v217, v3
	v_mul_f32_e32 v4, v217, v4
	v_mul_f32_e32 v5, v217, v5
	v_fma_f32 v2, v82, v2, v172
	v_fma_f32 v3, v83, v3, v173
	v_fma_f32 v4, v84, v4, v174
	v_fma_f32 v5, v85, v5, v175
	ds_write_b128 v248, v[2:5] offset:12480
	s_waitcnt lgkmcnt(0)
	ds_read_b128 v[66:69], v249 offset:0
	ds_read_b128 v[74:77], v249 offset:1024
	ds_read_b128 v[78:81], v249 offset:2048
	ds_read_b128 v[82:85], v249 offset:3072
	ds_read_b128 v[90:93], v249 offset:4096
	ds_read_b128 v[94:97], v249 offset:5120
	ds_read_b128 v[108:111], v249 offset:6144
	ds_read_b128 v[172:175], v249 offset:7168
	s_waitcnt lgkmcnt(7)
	global_store_dwordx4 v250, v[66:69], s[26:27] sc1
	s_waitcnt lgkmcnt(6)
	v_add_u32_e32 v251, 0x4000, v250
	global_store_dwordx4 v251, v[74:77], s[26:27] sc1
	s_waitcnt lgkmcnt(5)
	v_add_u32_e32 v251, 0x8000, v250
	global_store_dwordx4 v251, v[78:81], s[26:27] sc1
	s_waitcnt lgkmcnt(4)
	v_add_u32_e32 v251, 0xc000, v250
	global_store_dwordx4 v251, v[82:85], s[26:27] sc1
	s_waitcnt lgkmcnt(3)
	v_add_u32_e32 v251, 0x10000, v250
	global_store_dwordx4 v251, v[90:93], s[26:27] sc1
	s_waitcnt lgkmcnt(2)
	v_add_u32_e32 v251, 0x14000, v250
	global_store_dwordx4 v251, v[94:97], s[26:27] sc1
	s_waitcnt lgkmcnt(1)
	v_add_u32_e32 v251, 0x18000, v250
	global_store_dwordx4 v251, v[108:111], s[26:27] sc1
	s_waitcnt lgkmcnt(0)
	v_add_u32_e32 v251, 0x1c000, v250
	global_store_dwordx4 v251, v[172:175], s[26:27] sc1
	s_nop 1
	ds_read_b128 v[66:69], v249 offset:8192
	ds_read_b128 v[74:77], v249 offset:9216
	ds_read_b128 v[78:81], v249 offset:10240
	ds_read_b128 v[82:85], v249 offset:11264
	ds_read_b128 v[90:93], v249 offset:12288
	ds_read_b128 v[94:97], v249 offset:13312
	ds_read_b128 v[108:111], v249 offset:14336
	ds_read_b128 v[172:175], v249 offset:15360
	s_waitcnt lgkmcnt(7)
	v_add_u32_e32 v251, 0x20000, v250
	global_store_dwordx4 v251, v[66:69], s[26:27] sc1
	s_waitcnt lgkmcnt(6)
	v_add_u32_e32 v251, 0x24000, v250
	global_store_dwordx4 v251, v[74:77], s[26:27] sc1
	s_waitcnt lgkmcnt(5)
	v_add_u32_e32 v251, 0x28000, v250
	global_store_dwordx4 v251, v[78:81], s[26:27] sc1
	s_waitcnt lgkmcnt(4)
	v_add_u32_e32 v251, 0x2c000, v250
	global_store_dwordx4 v251, v[82:85], s[26:27] sc1
	s_waitcnt lgkmcnt(3)
	v_add_u32_e32 v251, 0x30000, v250
	global_store_dwordx4 v251, v[90:93], s[26:27] sc1
	s_waitcnt lgkmcnt(2)
	v_add_u32_e32 v251, 0x34000, v250
	global_store_dwordx4 v251, v[94:97], s[26:27] sc1
	s_waitcnt lgkmcnt(1)
	v_add_u32_e32 v251, 0x38000, v250
	global_store_dwordx4 v251, v[108:111], s[26:27] sc1
	s_waitcnt lgkmcnt(0)
	v_add_u32_e32 v251, 0x3c000, v250
	global_store_dwordx4 v251, v[172:175], s[26:27] sc1
	s_nop 1
	s_cmp_eq_u32 s53, 3
	s_cbranch_scc1 .Lln2_end
	s_add_u32 s34, s94, 0x7b48000
	s_addc_u32 s35, s95, 0
	s_waitcnt vmcnt(16)
	v_add_f32_e32 v226, 1.0, v226
	v_add_f32_e32 v227, 1.0, v227
	v_add_f32_e32 v228, 1.0, v228
	v_add_f32_e32 v229, 1.0, v229
	v_add_f32_e32 v230, 1.0, v230
	v_add_f32_e32 v231, 1.0, v231
	v_add_f32_e32 v232, 1.0, v232
	v_add_f32_e32 v233, 1.0, v233
	v_add_f32_e32 v234, 1.0, v234
	v_add_f32_e32 v235, 1.0, v235
	v_add_f32_e32 v236, 1.0, v236
	v_add_f32_e32 v237, 1.0, v237
	v_add_f32_e32 v238, 1.0, v238
	v_add_f32_e32 v239, 1.0, v239
	v_add_f32_e32 v240, 1.0, v240
	v_add_f32_e32 v241, 1.0, v241
	v_and_b32_e32 v251, 7, v246
	v_lshlrev_b32_e32 v251, 1, v251
	v_or_b32_e32 v218, 0, v247
	v_xor_b32_e32 v218, v218, v251
	v_lshlrev_b32_e32 v218, 3, v218
	v_lshl_add_u32 v218, v246, 7, v218
	v_add_u32_e32 v218, s54, v218
	v_or_b32_e32 v219, 4, v247
	v_xor_b32_e32 v219, v219, v251
	v_lshlrev_b32_e32 v219, 3, v219
	v_lshl_add_u32 v219, v246, 7, v219
	v_add_u32_e32 v219, s54, v219
	v_or_b32_e32 v220, 8, v247
	v_xor_b32_e32 v220, v220, v251
	v_lshlrev_b32_e32 v220, 3, v220
	v_lshl_add_u32 v220, v246, 7, v220
	v_add_u32_e32 v220, s54, v220
	v_or_b32_e32 v221, 12, v247
	v_xor_b32_e32 v221, v221, v251
	v_lshlrev_b32_e32 v221, 3, v221
	v_lshl_add_u32 v221, v246, 7, v221
	v_add_u32_e32 v221, s54, v221
	v_lshrrev_b32_e32 v248, 3, v222
	v_and_b32_e32 v251, 7, v222
	v_xor_b32_e32 v251, v251, v248
	v_add_u32_e32 v248, s50, v248
	v_lshlrev_b32_e32 v248, 11, v248
	v_lshl_add_u32 v248, v251, 4, v248
	s_lshl_b32 s55, s51, 1
	v_add_u32_e32 v248, s55, v248
	v_fma_f32 v62, v226, v62, v38
	v_fma_f32 v63, v227, v63, v39
	v_fma_f32 v64, v228, v64, v40
	v_fma_f32 v65, v229, v65, v41
	v_cvt_pk_bf16_f32 v62, v62, v63
	v_cvt_pk_bf16_f32 v63, v64, v65
	ds_write_b64 v218, v[62:63] offset:0
	v_fma_f32 v86, v230, v86, v42
	v_fma_f32 v87, v231, v87, v43
	v_fma_f32 v88, v232, v88, v44
	v_fma_f32 v89, v233, v89, v45
	v_cvt_pk_bf16_f32 v86, v86, v87
	v_cvt_pk_bf16_f32 v87, v88, v89
	ds_write_b64 v219, v[86:87] offset:0
	v_fma_f32 v70, v234, v70, v46
	v_fma_f32 v71, v235, v71, v47
	v_fma_f32 v72, v236, v72, v48
	v_fma_f32 v73, v237, v73, v49
	v_cvt_pk_bf16_f32 v70, v70, v71
	v_cvt_pk_bf16_f32 v71, v72, v73
	ds_write_b64 v220, v[70:71] offset:0
	v_fma_f32 v176, v238, v176, v50
	v_fma_f32 v177, v239, v177, v51
	v_fma_f32 v178, v240, v178, v52
	v_fma_f32 v179, v241, v179, v53
	v_cvt_pk_bf16_f32 v176, v176, v177
	v_cvt_pk_bf16_f32 v177, v178, v179
	ds_write_b64 v221, v[176:177] offset:0
	v_fma_f32 v202, v226, v202, v38
	v_fma_f32 v203, v227, v203, v39
	v_fma_f32 v204, v228, v204, v40
	v_fma_f32 v205, v229, v205, v41
	v_cvt_pk_bf16_f32 v202, v202, v203
	v_cvt_pk_bf16_f32 v203, v204, v205
	ds_write_b64 v218, v[202:203] offset:2048
	v_fma_f32 v54, v230, v54, v42
	v_fma_f32 v55, v231, v55, v43
	v_fma_f32 v56, v232, v56, v44
	v_fma_f32 v57, v233, v57, v45
	v_cvt_pk_bf16_f32 v54, v54, v55
	v_cvt_pk_bf16_f32 v55, v56, v57
	ds_write_b64 v219, v[54:55] offset:2048
	v_fma_f32 v58, v234, v58, v46
	v_fma_f32 v59, v235, v59, v47
	v_fma_f32 v60, v236, v60, v48
	v_fma_f32 v61, v237, v61, v49
	v_cvt_pk_bf16_f32 v58, v58, v59
	v_cvt_pk_bf16_f32 v59, v60, v61
	ds_write_b64 v220, v[58:59] offset:2048
	v_fma_f32 v34, v238, v34, v50
	v_fma_f32 v35, v239, v35, v51
	v_fma_f32 v36, v240, v36, v52
	v_fma_f32 v37, v241, v37, v53
	v_cvt_pk_bf16_f32 v34, v34, v35
	v_cvt_pk_bf16_f32 v35, v36, v37
	ds_write_b64 v221, v[34:35] offset:2048
	v_fma_f32 v30, v226, v30, v38
	v_fma_f32 v31, v227, v31, v39
	v_fma_f32 v32, v228, v32, v40
	v_fma_f32 v33, v229, v33, v41
	v_cvt_pk_bf16_f32 v30, v30, v31
	v_cvt_pk_bf16_f32 v31, v32, v33
	ds_write_b64 v218, v[30:31] offset:4096
	v_fma_f32 v26, v230, v26, v42
	v_fma_f32 v27, v231, v27, v43
	v_fma_f32 v28, v232, v28, v44
	v_fma_f32 v29, v233, v29, v45
	v_cvt_pk_bf16_f32 v26, v26, v27
	v_cvt_pk_bf16_f32 v27, v28, v29
	ds_write_b64 v219, v[26:27] offset:4096
	v_fma_f32 v22, v234, v22, v46
	v_fma_f32 v23, v235, v23, v47
	v_fma_f32 v24, v236, v24, v48
	v_fma_f32 v25, v237, v25, v49
	v_cvt_pk_bf16_f32 v22, v22, v23
	v_cvt_pk_bf16_f32 v23, v24, v25
	ds_write_b64 v220, v[22:23] offset:4096
	v_fma_f32 v18, v238, v18, v50
	v_fma_f32 v19, v239, v19, v51
	v_fma_f32 v20, v240, v20, v52
	v_fma_f32 v21, v241, v21, v53
	v_cvt_pk_bf16_f32 v18, v18, v19
	v_cvt_pk_bf16_f32 v19, v20, v21
	ds_write_b64 v221, v[18:19] offset:4096
	v_fma_f32 v14, v226, v14, v38
	v_fma_f32 v15, v227, v15, v39
	v_fma_f32 v16, v228, v16, v40
	v_fma_f32 v17, v229, v17, v41
	v_cvt_pk_bf16_f32 v14, v14, v15
	v_cvt_pk_bf16_f32 v15, v16, v17
	ds_write_b64 v218, v[14:15] offset:6144
	v_fma_f32 v10, v230, v10, v42
	v_fma_f32 v11, v231, v11, v43
	v_fma_f32 v12, v232, v12, v44
	v_fma_f32 v13, v233, v13, v45
	v_cvt_pk_bf16_f32 v10, v10, v11
	v_cvt_pk_bf16_f32 v11, v12, v13
	ds_write_b64 v219, v[10:11] offset:6144
	v_fma_f32 v6, v234, v6, v46
	v_fma_f32 v7, v235, v7, v47
	v_fma_f32 v8, v236, v8, v48
	v_fma_f32 v9, v237, v9, v49
	v_cvt_pk_bf16_f32 v6, v6, v7
	v_cvt_pk_bf16_f32 v7, v8, v9
	ds_write_b64 v220, v[6:7] offset:6144
	v_fma_f32 v2, v238, v2, v50
	v_fma_f32 v3, v239, v3, v51
	v_fma_f32 v4, v240, v4, v52
	v_fma_f32 v5, v241, v5, v53
	v_cvt_pk_bf16_f32 v2, v2, v3
	v_cvt_pk_bf16_f32 v3, v4, v5
	ds_write_b64 v221, v[2:3] offset:6144
	s_waitcnt lgkmcnt(0)
	ds_read_b128 v[66:69], v249 offset:0
	ds_read_b128 v[74:77], v249 offset:1024
	ds_read_b128 v[78:81], v249 offset:2048
	ds_read_b128 v[82:85], v249 offset:3072
	ds_read_b128 v[90:93], v249 offset:4096
	ds_read_b128 v[94:97], v249 offset:5120
	ds_read_b128 v[108:111], v249 offset:6144
	ds_read_b128 v[172:175], v249 offset:7168
	s_waitcnt lgkmcnt(7)
	global_store_dwordx4 v248, v[66:69], s[34:35]
	s_waitcnt lgkmcnt(6)
	v_add_u32_e32 v251, 0x4000, v248
	global_store_dwordx4 v251, v[74:77], s[34:35]
	s_waitcnt lgkmcnt(5)
	v_add_u32_e32 v251, 0x8000, v248
	global_store_dwordx4 v251, v[78:81], s[34:35]
	s_waitcnt lgkmcnt(4)
	v_add_u32_e32 v251, 0xc000, v248
	global_store_dwordx4 v251, v[82:85], s[34:35]
	s_waitcnt lgkmcnt(3)
	v_add_u32_e32 v251, 0x10000, v248
	global_store_dwordx4 v251, v[90:93], s[34:35]
	s_waitcnt lgkmcnt(2)
	v_add_u32_e32 v251, 0x14000, v248
	global_store_dwordx4 v251, v[94:97], s[34:35]
	s_waitcnt lgkmcnt(1)
	v_add_u32_e32 v251, 0x18000, v248
	global_store_dwordx4 v251, v[108:111], s[34:35]
	s_waitcnt lgkmcnt(0)
	v_add_u32_e32 v251, 0x1c000, v248
	global_store_dwordx4 v251, v[172:175], s[34:35]
